# S3 B prefetch by idle workgroups with plain (temporal) loads instead of nt
# speedup vs baseline: 1.0185x; 1.0034x over previous
; __device__ __forceinline__ KArgsPtr kargs() { KArgsPtr p = (KArgsPtr)__builtin_amdgcn_kernarg_segment_ptr(); asm volatile("" : "+s"(p)); return p; }
; #define GSYNC() do { XSYNC1(); if (PROBE_SYNC) XSYNC1(); } while (0)
; __global__ void __launch_bounds__(512, 2) fwd_megakernel(Args a_unused) {
;     ...
;           for (int un = vcu; un < NB * NHEAD * 16; un += G) { const int bh = un >> 4, qb = un & 15; attn_unit(lds, PROJ, OCAT, subg, lam, 1.0f - lam_init, bh >> 3, bh & 7, qb); } }
;         GSYNC();
;         { KArgsPtr ap = kargs();
;           const int vcu = (G % 8 == 0) ? (bx % 8) * (G / 8) + bx / 8 : bx;
;           pg8::GroupOrder S; S.init(NGRP, 2, 2, G, vcu, WSP(bf16_t, WS_ACOMB), WSP(bf16_t, WS_WCAT) + layer * WCAT_L, KA, KA, (size_t)RG * KA * 2, (size_t)512 * KA * 2);
;           EpiS3 E{WSP(bf16_t, WS_YG)};
;           pg8::gemm_phase(lds, KA, KA, KA, S, E);
.LBB0_473:
	s_cmpk_lt_u32 s75, 0x80
	s_cbranch_scc1 .Ls3b_prefetch_done
	s_load_dwordx2 s[4:5], s[0:1], 0xc8
	s_sub_i32 s8, s75, 0x80
	s_mul_i32 s8, s8, 0x60000
	s_mul_i32 s9, s80, 0x3000000
	s_add_i32 s8, s8, s9
	s_add_i32 s8, s8, 0x4a00000
	v_lshlrev_b32_e32 v0, 6, v234
	s_waitcnt lgkmcnt(0)
	s_add_u32 s4, s4, s8
	s_addc_u32 s5, s5, 0
	global_load_dword v1, v0, s[4:5]
	v_add_u32_e32 v0, 0x8000, v0
	global_load_dword v1, v0, s[4:5]
	v_add_u32_e32 v0, 0x8000, v0
	global_load_dword v1, v0, s[4:5]
	v_add_u32_e32 v0, 0x8000, v0
	global_load_dword v1, v0, s[4:5]
	v_add_u32_e32 v0, 0x8000, v0
	global_load_dword v1, v0, s[4:5]
	v_add_u32_e32 v0, 0x8000, v0
	global_load_dword v1, v0, s[4:5]
	v_add_u32_e32 v0, 0x8000, v0
	global_load_dword v1, v0, s[4:5]
	v_add_u32_e32 v0, 0x8000, v0
	global_load_dword v1, v0, s[4:5]
	v_add_u32_e32 v0, 0x8000, v0
	global_load_dword v1, v0, s[4:5]
	v_add_u32_e32 v0, 0x8000, v0
	global_load_dword v1, v0, s[4:5]
	v_add_u32_e32 v0, 0x8000, v0
	global_load_dword v1, v0, s[4:5]
	v_add_u32_e32 v0, 0x8000, v0
	global_load_dword v1, v0, s[4:5]
